# phase 0 weight prep: adaLN GEMV staging loads and fold-B operand loads batched under a single wait instead of one round trip per load group
# speedup vs baseline: 1.0649x; 1.0027x over previous
.LBB0_41:
	v_lshl_add_u64 v[76:77], v[72:73], 0, s[56:57]
	v_mov_b32_e32 v200, v76
	v_mov_b32_e32 v201, v77
	v_add_co_u32_e32 v202, vcc, 0x1000, v76
	s_nop 1
	v_addc_co_u32_e32 v203, vcc, 0, v77, vcc
	v_add_co_u32_e32 v204, vcc, 0x4000, v76
	s_nop 1
	v_addc_co_u32_e32 v205, vcc, 0, v77, vcc
	v_add_co_u32_e32 v206, vcc, 0x5000, v76
	s_nop 1
	v_addc_co_u32_e32 v207, vcc, 0, v77, vcc
	v_add_co_u32_e32 v208, vcc, 0x8000, v76
	s_nop 1
	v_addc_co_u32_e32 v209, vcc, 0, v77, vcc
	v_add_co_u32_e32 v210, vcc, 0x9000, v76
	s_nop 1
	v_addc_co_u32_e32 v211, vcc, 0, v77, vcc
	v_add_co_u32_e32 v212, vcc, 0xc000, v76
	s_nop 1
	v_addc_co_u32_e32 v213, vcc, 0, v77, vcc
	v_add_co_u32_e32 v214, vcc, 0xd000, v76
	s_nop 1
	v_addc_co_u32_e32 v215, vcc, 0, v77, vcc
	global_load_dword v216, v[200:201], off
	global_load_dword v217, v[200:201], off offset:1024
	global_load_dword v218, v[200:201], off offset:2048
	global_load_dword v219, v[200:201], off offset:3072
	global_load_dword v220, v[202:203], off
	global_load_dword v221, v[202:203], off offset:1024
	global_load_dword v222, v[202:203], off offset:2048
	global_load_dword v223, v[202:203], off offset:3072
	global_load_dword v224, v[204:205], off
	global_load_dword v225, v[204:205], off offset:1024
	global_load_dword v226, v[204:205], off offset:2048
	global_load_dword v227, v[204:205], off offset:3072
	global_load_dword v228, v[206:207], off
	global_load_dword v229, v[206:207], off offset:1024
	global_load_dword v230, v[206:207], off offset:2048
	global_load_dword v231, v[206:207], off offset:3072
	global_load_dword v232, v[208:209], off
	global_load_dword v233, v[208:209], off offset:1024
	global_load_dword v234, v[208:209], off offset:2048
	global_load_dword v235, v[208:209], off offset:3072
	global_load_dword v236, v[210:211], off
	global_load_dword v237, v[210:211], off offset:1024
	global_load_dword v238, v[210:211], off offset:2048
	global_load_dword v239, v[210:211], off offset:3072
	global_load_dword v240, v[212:213], off
	global_load_dword v241, v[212:213], off offset:1024
	global_load_dword v242, v[212:213], off offset:2048
	global_load_dword v243, v[212:213], off offset:3072
	global_load_dword v244, v[214:215], off
	global_load_dword v245, v[214:215], off offset:1024
	global_load_dword v246, v[214:215], off offset:2048
	global_load_dword v247, v[214:215], off offset:3072
	global_load_dwordx4 v[200:203], v[74:75], off offset:-128
	global_load_dwordx4 v[204:207], v[74:75], off offset:-112
	global_load_dwordx4 v[208:211], v[74:75], off offset:-64
	global_load_dwordx4 v[212:215], v[74:75], off offset:-48
	global_load_dwordx4 v[96:99], v[74:75], off offset:0
	global_load_dwordx4 v[100:103], v[74:75], off offset:16
	global_load_dwordx4 v[104:107], v[74:75], off offset:64
	global_load_dwordx4 v[248:251], v[74:75], off offset:80
	s_add_u32 s56, s56, 0x10000
	s_addc_u32 s57, s57, 0
	v_lshl_add_u64 v[74:75], v[74:75], 0, s[38:39]
	s_waitcnt vmcnt(0)
	v_cvt_pk_bf16_f32 v216, v216, v217
	v_cvt_pk_bf16_f32 v217, v218, v219
	v_cvt_pk_bf16_f32 v218, v220, v221
	v_cvt_pk_bf16_f32 v219, v222, v223
	v_cvt_pk_bf16_f32 v200, v200, v201
	v_cvt_pk_bf16_f32 v201, v202, v203
	v_cvt_pk_bf16_f32 v202, v204, v205
	v_cvt_pk_bf16_f32 v203, v206, v207
	v_cvt_pk_bf16_f32 v224, v224, v225
	v_cvt_pk_bf16_f32 v225, v226, v227
	v_cvt_pk_bf16_f32 v226, v228, v229
	v_cvt_pk_bf16_f32 v227, v230, v231
	v_cvt_pk_bf16_f32 v208, v208, v209
	v_cvt_pk_bf16_f32 v209, v210, v211
	v_cvt_pk_bf16_f32 v210, v212, v213
	v_cvt_pk_bf16_f32 v211, v214, v215
	v_cvt_pk_bf16_f32 v232, v232, v233
	v_cvt_pk_bf16_f32 v233, v234, v235
	v_cvt_pk_bf16_f32 v234, v236, v237
	v_cvt_pk_bf16_f32 v235, v238, v239
	v_cvt_pk_bf16_f32 v96, v96, v97
	v_cvt_pk_bf16_f32 v97, v98, v99
	v_cvt_pk_bf16_f32 v98, v100, v101
	v_cvt_pk_bf16_f32 v99, v102, v103
	v_cvt_pk_bf16_f32 v240, v240, v241
	v_cvt_pk_bf16_f32 v241, v242, v243
	v_cvt_pk_bf16_f32 v242, v244, v245
	v_cvt_pk_bf16_f32 v243, v246, v247
	v_cvt_pk_bf16_f32 v104, v104, v105
	v_cvt_pk_bf16_f32 v105, v106, v107
	v_cvt_pk_bf16_f32 v106, v248, v249
	v_cvt_pk_bf16_f32 v107, v250, v251
	s_nop 1
	v_mfma_f32_32x32x16_bf16 v[0:15], v[216:219], v[200:203], v[0:15]
	v_mfma_f32_32x32x16_bf16 v[0:15], v[224:227], v[208:211], v[0:15]
	v_mfma_f32_32x32x16_bf16 v[0:15], v[232:235], v[96:99], v[0:15]
	v_mfma_f32_32x32x16_bf16 v[0:15], v[240:243], v[104:107], v[0:15]
	s_cmp_eq_u32 s56, 0x40000
	s_cbranch_scc0 .LBB0_41
	v_and_b32_e32 v18, 0xffffff00, v65
	v_add_u32_e32 v18, v88, v18
	s_movk_i32 s56, 0xe0
	v_and_or_b32 v72, v65, s56, v18
	v_lshlrev_b32_e32 v18, 1, v95
	v_ashrrev_i32_e32 v73, 31, v72
	v_lshl_add_u64 v[74:75], v[20:21], 0, v[18:19]
	v_lshlrev_b64 v[76:77], 11, v[72:73]
	s_nop 2
	v_cvt_pk_bf16_f32 v0, v0, s0
	v_lshl_add_u64 v[76:77], v[74:75], 0, v[76:77]
	global_store_short v[76:77], v0, off
	v_or_b32_e32 v0, 1, v72
	v_cvt_pk_bf16_f32 v18, v1, s0
	v_ashrrev_i32_e32 v1, 31, v0
	v_lshlrev_b64 v[0:1], 11, v[0:1]
	v_lshl_add_u64 v[0:1], v[74:75], 0, v[0:1]
	global_store_short v[0:1], v18, off
	v_or_b32_e32 v0, 2, v72
	v_ashrrev_i32_e32 v1, 31, v0
	v_lshlrev_b64 v[0:1], 11, v[0:1]
	v_cvt_pk_bf16_f32 v2, v2, s0
	v_lshl_add_u64 v[0:1], v[74:75], 0, v[0:1]
	global_store_short v[0:1], v2, off
	v_or_b32_e32 v0, 3, v72
	v_ashrrev_i32_e32 v1, 31, v0
	v_lshlrev_b64 v[0:1], 11, v[0:1]
	v_cvt_pk_bf16_f32 v2, v3, s0
	v_lshl_add_u64 v[0:1], v[74:75], 0, v[0:1]
	global_store_short v[0:1], v2, off
	v_or_b32_e32 v0, 8, v72
	v_ashrrev_i32_e32 v1, 31, v0
	v_lshlrev_b64 v[0:1], 11, v[0:1]
	v_cvt_pk_bf16_f32 v2, v4, s0
	v_lshl_add_u64 v[0:1], v[74:75], 0, v[0:1]
	global_store_short v[0:1], v2, off
	v_or_b32_e32 v0, 9, v72
	v_ashrrev_i32_e32 v1, 31, v0
	v_lshlrev_b64 v[0:1], 11, v[0:1]
	v_cvt_pk_bf16_f32 v2, v5, s0
	v_lshl_add_u64 v[0:1], v[74:75], 0, v[0:1]
	global_store_short v[0:1], v2, off
	v_or_b32_e32 v0, 10, v72
	v_ashrrev_i32_e32 v1, 31, v0
	v_lshlrev_b64 v[0:1], 11, v[0:1]
	v_cvt_pk_bf16_f32 v2, v6, s0
	v_lshl_add_u64 v[0:1], v[74:75], 0, v[0:1]
	global_store_short v[0:1], v2, off
	v_or_b32_e32 v0, 11, v72
	v_ashrrev_i32_e32 v1, 31, v0
	v_lshlrev_b64 v[0:1], 11, v[0:1]
	v_cvt_pk_bf16_f32 v2, v7, s0
	v_lshl_add_u64 v[0:1], v[74:75], 0, v[0:1]
	global_store_short v[0:1], v2, off
	v_or_b32_e32 v0, 16, v72
	v_ashrrev_i32_e32 v1, 31, v0
	v_lshlrev_b64 v[0:1], 11, v[0:1]
	v_cvt_pk_bf16_f32 v2, v8, s0
	v_lshl_add_u64 v[0:1], v[74:75], 0, v[0:1]
	global_store_short v[0:1], v2, off
	v_or_b32_e32 v0, 17, v72
	v_ashrrev_i32_e32 v1, 31, v0
	v_lshlrev_b64 v[0:1], 11, v[0:1]
	v_cvt_pk_bf16_f32 v2, v9, s0
	v_lshl_add_u64 v[0:1], v[74:75], 0, v[0:1]
	global_store_short v[0:1], v2, off
	v_or_b32_e32 v0, 18, v72
	v_ashrrev_i32_e32 v1, 31, v0
	v_lshlrev_b64 v[0:1], 11, v[0:1]
	v_cvt_pk_bf16_f32 v2, v10, s0
	v_lshl_add_u64 v[0:1], v[74:75], 0, v[0:1]
	global_store_short v[0:1], v2, off
	v_or_b32_e32 v0, 19, v72
	v_ashrrev_i32_e32 v1, 31, v0
	v_lshlrev_b64 v[0:1], 11, v[0:1]
	v_cvt_pk_bf16_f32 v2, v11, s0
	v_lshl_add_u64 v[0:1], v[74:75], 0, v[0:1]
	global_store_short v[0:1], v2, off
	v_or_b32_e32 v0, 24, v72
	v_ashrrev_i32_e32 v1, 31, v0
	v_lshlrev_b64 v[0:1], 11, v[0:1]
	v_cvt_pk_bf16_f32 v2, v12, s0
	v_lshl_add_u64 v[0:1], v[74:75], 0, v[0:1]
	global_store_short v[0:1], v2, off
	v_or_b32_e32 v0, 25, v72
	v_ashrrev_i32_e32 v1, 31, v0
	v_lshlrev_b64 v[0:1], 11, v[0:1]
	v_cvt_pk_bf16_f32 v2, v13, s0
	v_lshl_add_u64 v[0:1], v[74:75], 0, v[0:1]
	global_store_short v[0:1], v2, off
	v_or_b32_e32 v0, 26, v72
	v_ashrrev_i32_e32 v1, 31, v0
	v_lshlrev_b64 v[0:1], 11, v[0:1]
	v_cvt_pk_bf16_f32 v2, v14, s0
	v_lshl_add_u64 v[0:1], v[74:75], 0, v[0:1]
	global_store_short v[0:1], v2, off
	v_or_b32_e32 v0, 27, v72
	v_ashrrev_i32_e32 v1, 31, v0
	v_lshlrev_b64 v[0:1], 11, v[0:1]
	v_cvt_pk_bf16_f32 v2, v15, s0
	v_lshl_add_u64 v[0:1], v[74:75], 0, v[0:1]
	global_store_short v[0:1], v2, off

.LBB0_47:
	s_mul_hi_i32 s56, s5, 0x2aaaaaab
	s_lshr_b32 s57, s56, 31
	s_ashr_i32 s56, s56, 4
	s_add_i32 s56, s56, s57
	s_mul_i32 s57, s56, 0x60
	s_sub_i32 s57, s5, s57
	v_lshl_or_b32 v12, s57, 5, v79
	s_ashr_i32 s57, s56, 31
	s_lshl_b64 s[60:61], s[56:57], 10
	v_lshl_add_u64 v[0:1], s[60:61], 0, v[24:25]
	s_waitcnt lgkmcnt(0)
	v_mov_b64_e32 v[2:3], s[42:43]
	v_mad_u64_u32 v[2:3], s[60:61], v0, s78, v[2:3]
	v_mad_i32_i24 v3, v1, s78, v3
	v_ashrrev_i32_e32 v13, 31, v12
	v_lshl_add_u64 v[0:1], v[12:13], 2, v[2:3]
	v_add_co_u32_e32 v2, vcc, s78, v0
	s_movk_i32 s57, 0x6000
	s_nop 0
	v_addc_co_u32_e32 v3, vcc, 0, v1, vcc
	global_load_dword v119, v[0:1], off
	global_load_dword v154, v[2:3], off
	v_add_co_u32_e32 v2, vcc, s57, v0
	s_mov_b32 s57, 0xf000
	s_nop 0
	v_addc_co_u32_e32 v3, vcc, 0, v1, vcc
	global_load_dword v153, v[2:3], off
	v_add_co_u32_e32 v2, vcc, s76, v0
	s_nop 1
	v_addc_co_u32_e32 v3, vcc, 0, v1, vcc
	global_load_dword v152, v[2:3], off
	v_add_co_u32_e32 v2, vcc, s77, v0
	s_nop 1
	v_addc_co_u32_e32 v3, vcc, 0, v1, vcc
	global_load_dword v151, v[2:3], off
	v_add_co_u32_e32 v2, vcc, s57, v0
	s_mov_b32 s57, 0x12000
	s_nop 0
	v_addc_co_u32_e32 v3, vcc, 0, v1, vcc
	global_load_dword v150, v[2:3], off
	v_add_co_u32_e32 v2, vcc, s57, v0
	s_mov_b32 s57, 0x15000
	s_nop 0
	v_addc_co_u32_e32 v3, vcc, 0, v1, vcc
	global_load_dword v149, v[2:3], off
	v_add_co_u32_e32 v2, vcc, s57, v0
	s_mov_b32 s57, 0x18000
	s_nop 0
	v_addc_co_u32_e32 v3, vcc, 0, v1, vcc
	global_load_dword v148, v[2:3], off
	v_add_co_u32_e32 v2, vcc, s57, v0
	s_mov_b32 s57, 0x1b000
	s_nop 0
	v_addc_co_u32_e32 v3, vcc, 0, v1, vcc
	global_load_dword v147, v[2:3], off
	v_add_co_u32_e32 v2, vcc, s57, v0
	s_mov_b32 s57, 0x1e000
	s_nop 0
	v_addc_co_u32_e32 v3, vcc, 0, v1, vcc
	global_load_dword v146, v[2:3], off
	v_add_co_u32_e32 v2, vcc, s57, v0
	s_mov_b32 s57, 0x21000
	s_nop 0
	v_addc_co_u32_e32 v3, vcc, 0, v1, vcc
	global_load_dword v145, v[2:3], off
	v_add_co_u32_e32 v2, vcc, s57, v0
	s_mov_b32 s57, 0x24000
	s_nop 0
	v_addc_co_u32_e32 v3, vcc, 0, v1, vcc
	global_load_dword v144, v[2:3], off
	v_add_co_u32_e32 v2, vcc, s57, v0
	s_mov_b32 s57, 0x27000
	s_nop 0
	v_addc_co_u32_e32 v3, vcc, 0, v1, vcc
	global_load_dword v143, v[2:3], off
	v_add_co_u32_e32 v2, vcc, s57, v0
	s_mov_b32 s57, 0x2a000
	s_nop 0
	v_addc_co_u32_e32 v3, vcc, 0, v1, vcc
	global_load_dword v142, v[2:3], off
	v_add_co_u32_e32 v2, vcc, s57, v0
	s_mov_b32 s57, 0x2d000
	s_nop 0
	v_addc_co_u32_e32 v3, vcc, 0, v1, vcc
	global_load_dword v141, v[2:3], off
	v_add_co_u32_e32 v2, vcc, s57, v0
	s_mov_b32 s57, 0x30000
	s_nop 0
	v_addc_co_u32_e32 v3, vcc, 0, v1, vcc
	global_load_dword v140, v[2:3], off
	v_add_co_u32_e32 v2, vcc, s57, v0
	s_mov_b32 s57, 0x33000
	s_nop 0
	v_addc_co_u32_e32 v3, vcc, 0, v1, vcc
	global_load_dword v139, v[2:3], off
	v_add_co_u32_e32 v2, vcc, s57, v0
	s_mov_b32 s57, 0x36000
	s_nop 0
	v_addc_co_u32_e32 v3, vcc, 0, v1, vcc
	global_load_dword v138, v[2:3], off
	v_add_co_u32_e32 v2, vcc, s57, v0
	s_mov_b32 s57, 0x39000
	s_nop 0
	v_addc_co_u32_e32 v3, vcc, 0, v1, vcc
	global_load_dword v137, v[2:3], off
	v_add_co_u32_e32 v2, vcc, s57, v0
	s_mov_b32 s57, 0x3c000
	s_nop 0
	v_addc_co_u32_e32 v3, vcc, 0, v1, vcc
	global_load_dword v136, v[2:3], off
	v_add_co_u32_e32 v2, vcc, s57, v0
	s_mov_b32 s57, 0x3f000
	s_nop 0
	v_addc_co_u32_e32 v3, vcc, 0, v1, vcc
	global_load_dword v135, v[2:3], off
	v_add_co_u32_e32 v2, vcc, s57, v0
	s_mov_b32 s57, 0x42000
	s_nop 0
	v_addc_co_u32_e32 v3, vcc, 0, v1, vcc
	global_load_dword v134, v[2:3], off
	v_add_co_u32_e32 v2, vcc, s57, v0
	s_mov_b32 s57, 0x45000
	s_nop 0
	v_addc_co_u32_e32 v3, vcc, 0, v1, vcc
	global_load_dword v133, v[2:3], off
	v_add_co_u32_e32 v2, vcc, s57, v0
	s_mov_b32 s57, 0x48000
	s_nop 0
	v_addc_co_u32_e32 v3, vcc, 0, v1, vcc
	global_load_dword v132, v[2:3], off
	v_add_co_u32_e32 v2, vcc, s57, v0
	s_mov_b32 s57, 0x4b000
	s_nop 0
	v_addc_co_u32_e32 v3, vcc, 0, v1, vcc
	global_load_dword v131, v[2:3], off
	v_add_co_u32_e32 v2, vcc, s57, v0
	s_mov_b32 s57, 0x4e000
	s_nop 0
	v_addc_co_u32_e32 v3, vcc, 0, v1, vcc
	global_load_dword v130, v[2:3], off
	v_add_co_u32_e32 v2, vcc, s57, v0
	s_mov_b32 s57, 0x51000
	s_nop 0
	v_addc_co_u32_e32 v3, vcc, 0, v1, vcc
	global_load_dword v129, v[2:3], off
	v_add_co_u32_e32 v2, vcc, s57, v0
	s_mov_b32 s57, 0x54000
	s_nop 0
	v_addc_co_u32_e32 v3, vcc, 0, v1, vcc
	global_load_dword v128, v[2:3], off
	v_add_co_u32_e32 v2, vcc, s57, v0
	s_mov_b32 s57, 0x57000
	s_nop 0
	v_addc_co_u32_e32 v3, vcc, 0, v1, vcc
	global_load_dword v127, v[2:3], off
	v_add_co_u32_e32 v2, vcc, s57, v0
	s_mov_b32 s57, 0x5a000
	s_nop 0
	v_addc_co_u32_e32 v3, vcc, 0, v1, vcc
	global_load_dword v126, v[2:3], off
	v_add_co_u32_e32 v2, vcc, s57, v0
	s_mov_b32 s57, 0x5d000
	s_nop 0
	v_addc_co_u32_e32 v3, vcc, 0, v1, vcc
	global_load_dword v125, v[2:3], off
	v_add_co_u32_e32 v2, vcc, s57, v0
	s_mov_b32 s57, 0x60000
	s_nop 0
	v_addc_co_u32_e32 v3, vcc, 0, v1, vcc
	global_load_dword v124, v[2:3], off
	v_add_co_u32_e32 v2, vcc, s57, v0
	s_mov_b32 s57, 0x63000
	s_nop 0
	v_addc_co_u32_e32 v3, vcc, 0, v1, vcc
	global_load_dword v123, v[2:3], off
	v_add_co_u32_e32 v2, vcc, s57, v0
	s_mov_b32 s57, 0x66000
	s_nop 0
	v_addc_co_u32_e32 v3, vcc, 0, v1, vcc
	global_load_dword v122, v[2:3], off
	v_add_co_u32_e32 v2, vcc, s57, v0
	s_mov_b32 s57, 0x69000
	s_nop 0
	v_addc_co_u32_e32 v3, vcc, 0, v1, vcc
	global_load_dword v121, v[2:3], off
	v_add_co_u32_e32 v2, vcc, s57, v0
	s_mov_b32 s57, 0x6c000
	s_nop 0
	v_addc_co_u32_e32 v3, vcc, 0, v1, vcc
	global_load_dword v120, v[2:3], off
	v_add_co_u32_e32 v2, vcc, s57, v0
	s_mov_b32 s57, 0x6f000
	s_nop 0
	v_addc_co_u32_e32 v3, vcc, 0, v1, vcc
	global_load_dword v111, v[2:3], off
	v_add_co_u32_e32 v2, vcc, s57, v0
	s_mov_b32 s57, 0x72000
	s_nop 0
	v_addc_co_u32_e32 v3, vcc, 0, v1, vcc
	global_load_dword v110, v[2:3], off
	v_add_co_u32_e32 v2, vcc, s57, v0
	s_mov_b32 s57, 0x75000
	s_nop 0
	v_addc_co_u32_e32 v3, vcc, 0, v1, vcc
	global_load_dword v109, v[2:3], off
	v_add_co_u32_e32 v2, vcc, s57, v0
	s_mov_b32 s57, 0x78000
	s_nop 0
	v_addc_co_u32_e32 v3, vcc, 0, v1, vcc
	global_load_dword v108, v[2:3], off
	v_add_co_u32_e32 v2, vcc, s57, v0
	s_mov_b32 s57, 0x7b000
	s_nop 0
	v_addc_co_u32_e32 v3, vcc, 0, v1, vcc
	global_load_dword v107, v[2:3], off
	v_add_co_u32_e32 v2, vcc, s57, v0
	s_mov_b32 s57, 0x7e000
	s_nop 0
	v_addc_co_u32_e32 v3, vcc, 0, v1, vcc
	global_load_dword v106, v[2:3], off
	v_add_co_u32_e32 v2, vcc, s57, v0
	s_mov_b32 s57, 0x81000
	s_nop 0
	v_addc_co_u32_e32 v3, vcc, 0, v1, vcc
	global_load_dword v105, v[2:3], off
	v_add_co_u32_e32 v2, vcc, s57, v0
	s_mov_b32 s57, 0x84000
	s_nop 0
	v_addc_co_u32_e32 v3, vcc, 0, v1, vcc
	global_load_dword v104, v[2:3], off
	v_add_co_u32_e32 v2, vcc, s57, v0
	s_nop 1
	v_addc_co_u32_e32 v3, vcc, 0, v1, vcc
	global_load_dword v103, v[2:3], off
	v_add_co_u32_e32 v2, vcc, s79, v0
	s_nop 1
	v_addc_co_u32_e32 v3, vcc, 0, v1, vcc
	global_load_dword v102, v[2:3], off
	v_add_co_u32_e32 v2, vcc, s80, v0
	s_nop 1
	v_addc_co_u32_e32 v3, vcc, 0, v1, vcc
	global_load_dword v101, v[2:3], off
	v_add_co_u32_e32 v2, vcc, s81, v0
	s_nop 1
	v_addc_co_u32_e32 v3, vcc, 0, v1, vcc
	global_load_dword v100, v[2:3], off
	v_add_co_u32_e32 v2, vcc, s82, v0
	s_nop 1
	v_addc_co_u32_e32 v3, vcc, 0, v1, vcc
	global_load_dword v99, v[2:3], off
	v_add_co_u32_e32 v2, vcc, s83, v0
	s_nop 1
	v_addc_co_u32_e32 v3, vcc, 0, v1, vcc
	global_load_dword v98, v[2:3], off
	v_add_co_u32_e32 v2, vcc, s84, v0
	s_nop 1
	v_addc_co_u32_e32 v3, vcc, 0, v1, vcc
	global_load_dword v97, v[2:3], off
	v_add_co_u32_e32 v2, vcc, s85, v0
	s_nop 1
	v_addc_co_u32_e32 v3, vcc, 0, v1, vcc
	global_load_dword v96, v[2:3], off
	v_add_co_u32_e32 v2, vcc, s86, v0
	s_nop 1
	v_addc_co_u32_e32 v3, vcc, 0, v1, vcc
	global_load_dword v95, v[2:3], off
	v_add_co_u32_e32 v2, vcc, s87, v0
	s_nop 1
	v_addc_co_u32_e32 v3, vcc, 0, v1, vcc
	global_load_dword v77, v[2:3], off
	v_add_co_u32_e32 v2, vcc, s88, v0
	s_nop 1
	v_addc_co_u32_e32 v3, vcc, 0, v1, vcc
	global_load_dword v76, v[2:3], off
	v_add_co_u32_e32 v2, vcc, s89, v0
	s_nop 1
	v_addc_co_u32_e32 v3, vcc, 0, v1, vcc
	global_load_dword v75, v[2:3], off
	v_add_co_u32_e32 v2, vcc, s90, v0
	s_nop 1
	v_addc_co_u32_e32 v3, vcc, 0, v1, vcc
	global_load_dword v74, v[2:3], off
	v_add_co_u32_e32 v2, vcc, s91, v0
	s_nop 1
	v_addc_co_u32_e32 v3, vcc, 0, v1, vcc
	global_load_dword v73, v[2:3], off
	v_add_co_u32_e32 v2, vcc, s92, v0
	s_nop 1
	v_addc_co_u32_e32 v3, vcc, 0, v1, vcc
	global_load_dword v72, v[2:3], off
	v_add_co_u32_e32 v2, vcc, s93, v0
	s_nop 1
	v_addc_co_u32_e32 v3, vcc, 0, v1, vcc
	global_load_dword v65, v[2:3], off
	v_add_co_u32_e32 v2, vcc, s96, v0
	s_nop 1
	v_addc_co_u32_e32 v3, vcc, 0, v1, vcc
	global_load_dword v18, v[2:3], off
	v_add_co_u32_e32 v2, vcc, s97, v0
	s_nop 1
	v_addc_co_u32_e32 v3, vcc, 0, v1, vcc
	global_load_dword v15, v[2:3], off
	v_add_co_u32_e32 v2, vcc, s95, v0
	s_nop 1
	v_addc_co_u32_e32 v3, vcc, 0, v1, vcc
	v_add_co_u32_e32 v0, vcc, s4, v0
	global_load_dword v14, v[2:3], off
	s_nop 0
	v_addc_co_u32_e32 v1, vcc, 0, v1, vcc
	global_load_dword v13, v[0:1], off
	s_nop 0
	global_load_dword v200, v[32:33], off
	global_load_dword v201, v[32:33], off offset:2048
	global_load_dword v202, v[34:35], off
	global_load_dword v203, v[36:37], off
	global_load_dword v204, v[68:69], off
	global_load_dword v205, v[38:39], off
	global_load_dword v206, v[40:41], off
	global_load_dword v207, v[42:43], off
	global_load_dword v208, v[44:45], off
	global_load_dword v209, v[46:47], off
	global_load_dword v210, v[48:49], off
	global_load_dword v211, v[50:51], off
	global_load_dword v212, v[52:53], off
	global_load_dword v213, v[54:55], off
	global_load_dword v214, v[56:57], off
	global_load_dword v215, v[66:67], off
	s_waitcnt vmcnt(0)
	v_mul_f32_e32 v216, 0xbfb8aa3b, v200
	v_mul_f32_e32 v217, 0xbfb8aa3b, v201
	v_mul_f32_e32 v218, 0xbfb8aa3b, v202
	v_mul_f32_e32 v219, 0xbfb8aa3b, v203
	v_mul_f32_e32 v220, 0xbfb8aa3b, v204
	v_mul_f32_e32 v221, 0xbfb8aa3b, v205
	v_mul_f32_e32 v222, 0xbfb8aa3b, v206
	v_mul_f32_e32 v223, 0xbfb8aa3b, v207
	v_mul_f32_e32 v224, 0xbfb8aa3b, v208
	v_mul_f32_e32 v225, 0xbfb8aa3b, v209
	v_mul_f32_e32 v226, 0xbfb8aa3b, v210
	v_mul_f32_e32 v227, 0xbfb8aa3b, v211
	v_mul_f32_e32 v228, 0xbfb8aa3b, v212
	v_mul_f32_e32 v229, 0xbfb8aa3b, v213
	v_mul_f32_e32 v230, 0xbfb8aa3b, v214
	v_mul_f32_e32 v231, 0xbfb8aa3b, v215
	v_exp_f32_e32 v216, v216
	v_exp_f32_e32 v217, v217
	v_exp_f32_e32 v218, v218
	v_exp_f32_e32 v219, v219
	v_exp_f32_e32 v220, v220
	v_exp_f32_e32 v221, v221
	v_exp_f32_e32 v222, v222
	v_exp_f32_e32 v223, v223
	v_exp_f32_e32 v224, v224
	v_exp_f32_e32 v225, v225
	v_exp_f32_e32 v226, v226
	v_exp_f32_e32 v227, v227
	v_exp_f32_e32 v228, v228
	v_exp_f32_e32 v229, v229
	v_exp_f32_e32 v230, v230
	v_exp_f32_e32 v231, v231
	v_add_f32_e32 v216, 1.0, v216
	v_add_f32_e32 v217, 1.0, v217
	v_add_f32_e32 v218, 1.0, v218
	v_add_f32_e32 v219, 1.0, v219
	v_add_f32_e32 v220, 1.0, v220
	v_add_f32_e32 v221, 1.0, v221
	v_add_f32_e32 v222, 1.0, v222
	v_add_f32_e32 v223, 1.0, v223
	v_add_f32_e32 v224, 1.0, v224
	v_add_f32_e32 v225, 1.0, v225
	v_add_f32_e32 v226, 1.0, v226
	v_add_f32_e32 v227, 1.0, v227
	v_add_f32_e32 v228, 1.0, v228
	v_add_f32_e32 v229, 1.0, v229
	v_add_f32_e32 v230, 1.0, v230
	v_add_f32_e32 v231, 1.0, v231
	v_rcp_f32_e32 v216, v216
	v_rcp_f32_e32 v217, v217
	v_rcp_f32_e32 v218, v218
	v_rcp_f32_e32 v219, v219
	v_rcp_f32_e32 v220, v220
	v_rcp_f32_e32 v221, v221
	v_rcp_f32_e32 v222, v222
	v_rcp_f32_e32 v223, v223
	v_rcp_f32_e32 v224, v224
	v_rcp_f32_e32 v225, v225
	v_rcp_f32_e32 v226, v226
	v_rcp_f32_e32 v227, v227
	v_rcp_f32_e32 v228, v228
	v_rcp_f32_e32 v229, v229
	v_rcp_f32_e32 v230, v230
	v_rcp_f32_e32 v231, v231
	v_mul_f32_e32 v200, v200, v216
	v_mul_f32_e32 v201, v201, v217
	v_mul_f32_e32 v202, v202, v218
	v_mul_f32_e32 v203, v203, v219
	v_mul_f32_e32 v204, v204, v220
	v_mul_f32_e32 v205, v205, v221
	v_mul_f32_e32 v206, v206, v222
	v_mul_f32_e32 v207, v207, v223
	v_mul_f32_e32 v208, v208, v224
	v_mul_f32_e32 v209, v209, v225
	v_mul_f32_e32 v210, v210, v226
	v_mul_f32_e32 v211, v211, v227
	v_mul_f32_e32 v212, v212, v228
	v_mul_f32_e32 v213, v213, v229
	v_mul_f32_e32 v214, v214, v230
	v_mul_f32_e32 v215, v215, v231
	ds_write2st64_b32 v91, v200, v201 offset1:8
	ds_write2st64_b32 v91, v202, v203 offset0:16 offset1:24
	ds_write2st64_b32 v91, v204, v205 offset0:32 offset1:40
	ds_write2st64_b32 v91, v206, v207 offset0:48 offset1:56
	ds_write2st64_b32 v91, v208, v209 offset0:64 offset1:72
	ds_write2st64_b32 v91, v210, v211 offset0:80 offset1:88
	ds_write2st64_b32 v91, v212, v213 offset0:96 offset1:104
	ds_write2st64_b32 v91, v214, v215 offset0:112 offset1:120
	v_mov_b32_e32 v0, v214
	v_mov_b32_e32 v1, v215
	s_waitcnt lgkmcnt(0)
	s_barrier
	ds_read_b128 v[160:163], v90
	ds_read_b128 v[8:11], v90 offset:16
	ds_read_b128 v[4:7], v90 offset:32
	ds_read_b128 v[0:3], v90 offset:48
	ds_read_b128 v[164:167], v90 offset:4096
	s_waitcnt lgkmcnt(4)
	v_fma_f32 v112, v119, v160, 0
	v_fmac_f32_e32 v112, v154, v161
	v_fmac_f32_e32 v112, v153, v162
	v_fmac_f32_e32 v112, v152, v163
	s_waitcnt lgkmcnt(3)
	v_fmac_f32_e32 v112, v151, v8
	v_fmac_f32_e32 v112, v150, v9
	v_fmac_f32_e32 v112, v149, v10
	v_fmac_f32_e32 v112, v148, v11
	s_waitcnt lgkmcnt(2)
	v_fmac_f32_e32 v112, v147, v4
	v_fmac_f32_e32 v112, v146, v5
	ds_read_b128 v[168:171], v90 offset:8192
	ds_read_b128 v[172:175], v90 offset:12288
	v_fmac_f32_e32 v112, v145, v6
	v_fmac_f32_e32 v112, v144, v7
	s_waitcnt lgkmcnt(3)
	v_fmac_f32_e32 v112, v143, v0
	ds_read_b128 v[176:179], v90 offset:16384
	ds_read_b128 v[180:183], v90 offset:20480
	v_fmac_f32_e32 v112, v142, v1
	v_fmac_f32_e32 v112, v141, v2
	s_waitcnt lgkmcnt(2)
	v_fma_f32 v115, v119, v172, 0
	v_fmac_f32_e32 v112, v140, v3
	ds_read_b128 v[0:3], v90 offset:64
	v_fma_f32 v113, v119, v164, 0
	ds_read_b128 v[192:195], v90 offset:24576
	ds_read_b128 v[196:199], v90 offset:28672
	v_fmac_f32_e32 v113, v154, v165
	v_fmac_f32_e32 v115, v154, v173
	v_fmac_f32_e32 v113, v153, v166
	v_fmac_f32_e32 v115, v153, v174
	v_fmac_f32_e32 v113, v152, v167
	v_fmac_f32_e32 v115, v152, v175
	ds_read_b128 v[164:167], v90 offset:12304
	s_waitcnt lgkmcnt(5)
	v_fma_f32 v116, v119, v176, 0
	ds_read_b128 v[172:175], v90 offset:20496
	s_waitcnt lgkmcnt(5)
	v_fma_f32 v117, v119, v180, 0
	v_fmac_f32_e32 v116, v154, v177
	v_fmac_f32_e32 v117, v154, v181
	v_fmac_f32_e32 v116, v153, v178
	v_fmac_f32_e32 v117, v153, v182
	v_fma_f32 v114, v119, v168, 0
	v_fmac_f32_e32 v116, v152, v179
	v_fmac_f32_e32 v117, v152, v183
	ds_read_b128 v[176:179], v90 offset:24592
	s_waitcnt lgkmcnt(4)
	v_fma_f32 v118, v119, v192, 0
	ds_read_b128 v[180:183], v90 offset:28688
	s_waitcnt lgkmcnt(4)
	v_fma_f32 v119, v119, v196, 0
	v_fmac_f32_e32 v112, v139, v0
	v_fmac_f32_e32 v114, v154, v169
	v_fmac_f32_e32 v118, v154, v193
	v_fmac_f32_e32 v119, v154, v197
	v_fmac_f32_e32 v112, v138, v1
	v_fmac_f32_e32 v114, v153, v170
	v_fmac_f32_e32 v118, v153, v194
	v_fmac_f32_e32 v119, v153, v198
	v_fmac_f32_e32 v112, v137, v2
	v_fmac_f32_e32 v114, v152, v171
	v_fmac_f32_e32 v118, v152, v195
	v_fmac_f32_e32 v119, v152, v199
	ds_read_b128 v[152:155], v90 offset:4112
	v_fmac_f32_e32 v112, v136, v3
	ds_read_b128 v[0:3], v90 offset:80
	ds_read_b128 v[8:11], v90 offset:4128
	ds_read_b128 v[4:7], v90 offset:4144
	s_waitcnt lgkmcnt(3)
	v_fmac_f32_e32 v113, v151, v152
	v_fmac_f32_e32 v113, v150, v153
	s_waitcnt lgkmcnt(2)
	v_fmac_f32_e32 v112, v135, v0
	v_fmac_f32_e32 v112, v134, v1
	v_fmac_f32_e32 v112, v133, v2
	v_fmac_f32_e32 v112, v132, v3
	ds_read_b128 v[0:3], v90 offset:96
	v_fmac_f32_e32 v113, v149, v154
	v_fmac_f32_e32 v113, v148, v155
	s_waitcnt lgkmcnt(2)
	v_fmac_f32_e32 v113, v147, v8
	v_fmac_f32_e32 v113, v146, v9
	s_waitcnt lgkmcnt(0)
	v_fmac_f32_e32 v112, v131, v0
	v_fmac_f32_e32 v113, v145, v10
	v_fmac_f32_e32 v112, v130, v1
	v_fmac_f32_e32 v113, v144, v11
	v_fmac_f32_e32 v112, v129, v2
	v_fmac_f32_e32 v112, v128, v3
	ds_read_b128 v[0:3], v90 offset:112
	v_fmac_f32_e32 v113, v143, v4
	v_fmac_f32_e32 v113, v142, v5
	v_fmac_f32_e32 v113, v141, v6
	v_fmac_f32_e32 v113, v140, v7
	ds_read_b128 v[4:7], v90 offset:4160
	s_waitcnt lgkmcnt(1)
	v_fmac_f32_e32 v112, v127, v0
	v_fmac_f32_e32 v112, v126, v1
	v_fmac_f32_e32 v112, v125, v2
	v_fmac_f32_e32 v112, v124, v3
	ds_read_b128 v[0:3], v90 offset:128
	s_waitcnt lgkmcnt(1)
	v_fmac_f32_e32 v113, v139, v4
	v_fmac_f32_e32 v113, v138, v5
	v_fmac_f32_e32 v113, v137, v6
	v_fmac_f32_e32 v113, v136, v7
	ds_read_b128 v[4:7], v90 offset:4176
	s_waitcnt lgkmcnt(1)
	v_fmac_f32_e32 v112, v123, v0
	v_fmac_f32_e32 v112, v122, v1
	v_fmac_f32_e32 v112, v121, v2
	v_fmac_f32_e32 v112, v120, v3
	ds_read_b128 v[0:3], v90 offset:144
	s_waitcnt lgkmcnt(1)
	v_fmac_f32_e32 v113, v135, v4
	v_fmac_f32_e32 v113, v134, v5
	v_fmac_f32_e32 v113, v133, v6
	v_fmac_f32_e32 v113, v132, v7
	ds_read_b128 v[4:7], v90 offset:4192
	s_waitcnt lgkmcnt(1)
	v_fmac_f32_e32 v112, v111, v0
	v_fmac_f32_e32 v112, v110, v1
	v_fmac_f32_e32 v112, v109, v2
	v_fmac_f32_e32 v112, v108, v3
	ds_read_b128 v[0:3], v90 offset:160
	s_waitcnt lgkmcnt(1)
	v_fmac_f32_e32 v113, v131, v4
	v_fmac_f32_e32 v113, v130, v5
	v_fmac_f32_e32 v113, v129, v6
	v_fmac_f32_e32 v113, v128, v7
	ds_read_b128 v[4:7], v90 offset:4208
	s_waitcnt lgkmcnt(1)
	v_fmac_f32_e32 v112, v107, v0
	v_fmac_f32_e32 v112, v106, v1
	v_fmac_f32_e32 v112, v105, v2
	v_fmac_f32_e32 v112, v104, v3
	ds_read_b128 v[0:3], v90 offset:176
	s_waitcnt lgkmcnt(1)
	v_fmac_f32_e32 v113, v127, v4
	v_fmac_f32_e32 v113, v126, v5
	v_fmac_f32_e32 v113, v125, v6
	v_fmac_f32_e32 v113, v124, v7
	ds_read_b128 v[4:7], v90 offset:4224
	s_waitcnt lgkmcnt(1)
	v_fmac_f32_e32 v112, v103, v0
	v_fmac_f32_e32 v112, v102, v1
	v_fmac_f32_e32 v112, v101, v2
	v_fmac_f32_e32 v112, v100, v3
	ds_read_b128 v[0:3], v90 offset:192
	s_waitcnt lgkmcnt(1)
	v_fmac_f32_e32 v113, v123, v4
	v_fmac_f32_e32 v113, v122, v5
	v_fmac_f32_e32 v113, v121, v6
	v_fmac_f32_e32 v113, v120, v7
	ds_read_b128 v[4:7], v90 offset:4240
	s_waitcnt lgkmcnt(1)
	v_fmac_f32_e32 v112, v99, v0
	v_fmac_f32_e32 v112, v98, v1
	v_fmac_f32_e32 v112, v97, v2
	v_fmac_f32_e32 v112, v96, v3
	ds_read_b128 v[0:3], v90 offset:208
	s_waitcnt lgkmcnt(1)
	v_fmac_f32_e32 v113, v111, v4
	v_fmac_f32_e32 v113, v110, v5
	v_fmac_f32_e32 v113, v109, v6
	v_fmac_f32_e32 v113, v108, v7
	ds_read_b128 v[4:7], v90 offset:4256
	s_waitcnt lgkmcnt(1)
	v_fmac_f32_e32 v112, v95, v0
	v_fmac_f32_e32 v112, v77, v1
	v_fmac_f32_e32 v112, v76, v2
	v_fmac_f32_e32 v112, v75, v3
	ds_read_b128 v[0:3], v90 offset:224
	s_waitcnt lgkmcnt(1)
	v_fmac_f32_e32 v113, v107, v4
	v_fmac_f32_e32 v113, v106, v5
	v_fmac_f32_e32 v113, v105, v6
	v_fmac_f32_e32 v113, v104, v7
	ds_read_b128 v[4:7], v90 offset:4272
	s_waitcnt lgkmcnt(1)
	v_fmac_f32_e32 v112, v74, v0
	v_fmac_f32_e32 v112, v73, v1
	ds_read_b128 v[160:163], v90 offset:8208
	v_fmac_f32_e32 v112, v72, v2
	v_fmac_f32_e32 v112, v65, v3
	ds_read_b128 v[0:3], v90 offset:240
	s_waitcnt lgkmcnt(2)
	v_fmac_f32_e32 v113, v103, v4
	v_fmac_f32_e32 v113, v102, v5
	ds_read_b128 v[168:171], v90 offset:16400
	v_fmac_f32_e32 v113, v101, v6
	v_fmac_f32_e32 v113, v100, v7
	ds_read_b128 v[4:7], v90 offset:4288
	s_waitcnt lgkmcnt(3)
	v_fmac_f32_e32 v114, v151, v160
	v_fmac_f32_e32 v114, v150, v161
	v_fmac_f32_e32 v114, v149, v162
	v_fmac_f32_e32 v115, v151, v164
	v_fmac_f32_e32 v117, v151, v172
	v_fmac_f32_e32 v118, v151, v176
	v_fmac_f32_e32 v119, v151, v180
	v_fmac_f32_e32 v114, v148, v163
	ds_read_b128 v[160:163], v90 offset:16416
	s_waitcnt lgkmcnt(2)
	v_fmac_f32_e32 v116, v151, v168
	v_fmac_f32_e32 v115, v150, v165
	v_fmac_f32_e32 v116, v150, v169
	v_fmac_f32_e32 v117, v150, v173
	v_fmac_f32_e32 v118, v150, v177
	v_fmac_f32_e32 v119, v150, v181
	s_waitcnt lgkmcnt(1)
	v_fmac_f32_e32 v113, v99, v4
	v_fmac_f32_e32 v115, v149, v166
	v_fmac_f32_e32 v116, v149, v170
	v_fmac_f32_e32 v117, v149, v174
	v_fmac_f32_e32 v118, v149, v178
	v_fmac_f32_e32 v119, v149, v182
	v_fmac_f32_e32 v113, v98, v5
	v_fmac_f32_e32 v115, v148, v167
	v_fmac_f32_e32 v116, v148, v171
	v_fmac_f32_e32 v117, v148, v175
	v_fmac_f32_e32 v118, v148, v179
	v_fmac_f32_e32 v119, v148, v183
	ds_read_b128 v[148:151], v90 offset:8224
	v_fmac_f32_e32 v113, v97, v6
	v_fmac_f32_e32 v113, v96, v7
	ds_read_b128 v[4:7], v90 offset:4304
	ds_read_b128 v[8:11], v90 offset:8240
	s_waitcnt lgkmcnt(2)
	v_fmac_f32_e32 v114, v147, v148
	v_fmac_f32_e32 v114, v146, v149
	v_fmac_f32_e32 v114, v145, v150
	s_waitcnt lgkmcnt(1)
	v_fmac_f32_e32 v113, v95, v4
	v_fmac_f32_e32 v113, v77, v5
	v_fmac_f32_e32 v114, v144, v151
	v_fmac_f32_e32 v113, v76, v6
	v_fmac_f32_e32 v113, v75, v7
	ds_read_b128 v[4:7], v90 offset:4320
	s_waitcnt lgkmcnt(1)
	v_fmac_f32_e32 v114, v143, v8
	v_fmac_f32_e32 v114, v142, v9
	v_fmac_f32_e32 v114, v141, v10
	v_fmac_f32_e32 v114, v140, v11
	ds_read_b128 v[8:11], v90 offset:8256
	s_waitcnt lgkmcnt(1)
	v_fmac_f32_e32 v113, v74, v4
	ds_read_b128 v[152:155], v90 offset:12320
	v_fmac_f32_e32 v113, v73, v5
	v_fmac_f32_e32 v113, v72, v6
	v_fmac_f32_e32 v113, v65, v7
	ds_read_b128 v[4:7], v90 offset:4336
	s_waitcnt lgkmcnt(2)
	v_fmac_f32_e32 v114, v139, v8
	ds_read_b128 v[164:167], v90 offset:20512
	v_fmac_f32_e32 v114, v138, v9
	v_fmac_f32_e32 v114, v137, v10
	v_fmac_f32_e32 v114, v136, v11
	ds_read_b128 v[8:11], v90 offset:8272
	s_waitcnt lgkmcnt(3)
	v_fmac_f32_e32 v115, v147, v152
	ds_read_b128 v[168:171], v90 offset:24608
	ds_read_b128 v[172:175], v90 offset:28704
	v_fmac_f32_e32 v115, v146, v153
	v_fmac_f32_e32 v115, v145, v154
	v_fmac_f32_e32 v116, v147, v160
	v_fmac_f32_e32 v115, v144, v155
	ds_read_b128 v[152:155], v90 offset:20528
	s_waitcnt lgkmcnt(4)
	v_fmac_f32_e32 v117, v147, v164
	v_fmac_f32_e32 v116, v146, v161
	v_fmac_f32_e32 v117, v146, v165
	v_fmac_f32_e32 v116, v145, v162
	v_fmac_f32_e32 v117, v145, v166
	v_fmac_f32_e32 v116, v144, v163
	v_fmac_f32_e32 v117, v144, v167
	ds_read_b128 v[160:163], v90 offset:24624
	s_waitcnt lgkmcnt(3)
	v_fmac_f32_e32 v118, v147, v168
	ds_read_b128 v[164:167], v90 offset:28720
	s_waitcnt lgkmcnt(3)
	v_fmac_f32_e32 v119, v147, v172
	v_fmac_f32_e32 v118, v146, v169
	v_fmac_f32_e32 v119, v146, v173
	v_fmac_f32_e32 v118, v145, v170
	v_fmac_f32_e32 v119, v145, v174
	v_fmac_f32_e32 v118, v144, v171
	v_fmac_f32_e32 v119, v144, v175
	ds_read_b128 v[144:147], v90 offset:12336
	v_fmac_f32_e32 v114, v135, v8
	ds_read_b128 v[148:151], v90 offset:16432
	v_fmac_f32_e32 v114, v134, v9
	v_fmac_f32_e32 v114, v133, v10
	v_fmac_f32_e32 v114, v132, v11
	ds_read_b128 v[8:11], v90 offset:8288
	s_waitcnt lgkmcnt(2)
	v_fmac_f32_e32 v115, v143, v144
	v_fmac_f32_e32 v115, v142, v145
	v_fmac_f32_e32 v115, v141, v146
	v_fmac_f32_e32 v115, v140, v147
	ds_read_b128 v[144:147], v90 offset:16448
	s_waitcnt lgkmcnt(2)
	v_fmac_f32_e32 v116, v143, v148
	v_fmac_f32_e32 v116, v142, v149
	v_fmac_f32_e32 v116, v141, v150
	v_fmac_f32_e32 v117, v143, v152
	v_fmac_f32_e32 v116, v140, v151
	ds_read_b128 v[148:151], v90 offset:20544
	v_fmac_f32_e32 v117, v142, v153
	v_fmac_f32_e32 v117, v141, v154
	s_waitcnt lgkmcnt(1)
	v_fmac_f32_e32 v116, v139, v144
	v_fmac_f32_e32 v118, v143, v160
	v_fmac_f32_e32 v119, v143, v164
	v_fmac_f32_e32 v117, v140, v155
	ds_read_b128 v[152:155], v90 offset:24640
	v_fmac_f32_e32 v116, v138, v145
	v_fmac_f32_e32 v118, v142, v161
	v_fmac_f32_e32 v119, v142, v165
	v_fmac_f32_e32 v116, v137, v146
	v_fmac_f32_e32 v118, v141, v162
	v_fmac_f32_e32 v119, v141, v166
	v_fmac_f32_e32 v116, v136, v147
	ds_read_b128 v[144:147], v90 offset:20560
	s_waitcnt lgkmcnt(2)
	v_fmac_f32_e32 v117, v139, v148
	v_fmac_f32_e32 v118, v140, v163
	v_fmac_f32_e32 v119, v140, v167
	ds_read_b128 v[140:143], v90 offset:12352
	ds_read_b128 v[160:163], v90 offset:28736
	v_fmac_f32_e32 v117, v138, v149
	v_fmac_f32_e32 v117, v137, v150
	v_fmac_f32_e32 v117, v136, v151
	ds_read_b128 v[148:151], v90 offset:24656
	s_waitcnt lgkmcnt(4)
	v_fmac_f32_e32 v118, v139, v152
	v_fmac_f32_e32 v114, v131, v8
	v_fmac_f32_e32 v118, v138, v153
	v_fmac_f32_e32 v114, v130, v9
	v_fmac_f32_e32 v118, v137, v154
	v_fmac_f32_e32 v114, v129, v10
	v_fmac_f32_e32 v118, v136, v155
	ds_read_b128 v[152:155], v90 offset:28752
	s_waitcnt lgkmcnt(2)
	v_fmac_f32_e32 v119, v139, v160
	v_fmac_f32_e32 v114, v128, v11
	ds_read_b128 v[8:11], v90 offset:8304
	v_fmac_f32_e32 v115, v139, v140
	v_fmac_f32_e32 v115, v138, v141
	v_fmac_f32_e32 v119, v138, v161
	v_fmac_f32_e32 v115, v137, v142
	v_fmac_f32_e32 v119, v137, v162
	v_fmac_f32_e32 v115, v136, v143
	v_fmac_f32_e32 v119, v136, v163
	ds_read_b128 v[136:139], v90 offset:12368
	s_waitcnt lgkmcnt(1)
	v_fmac_f32_e32 v114, v127, v8
	ds_read_b128 v[140:143], v90 offset:16464
	v_fmac_f32_e32 v114, v126, v9
	v_fmac_f32_e32 v114, v125, v10
	v_fmac_f32_e32 v114, v124, v11
	ds_read_b128 v[8:11], v90 offset:8320
	s_waitcnt lgkmcnt(2)
	v_fmac_f32_e32 v115, v135, v136
	v_fmac_f32_e32 v115, v134, v137
	v_fmac_f32_e32 v115, v133, v138
	v_fmac_f32_e32 v115, v132, v139
	ds_read_b128 v[136:139], v90 offset:16480
	s_waitcnt lgkmcnt(2)
	v_fmac_f32_e32 v116, v135, v140
	v_fmac_f32_e32 v116, v134, v141
	v_fmac_f32_e32 v116, v133, v142
	v_fmac_f32_e32 v117, v135, v144
	v_fmac_f32_e32 v116, v132, v143
	ds_read_b128 v[140:143], v90 offset:20576
	v_fmac_f32_e32 v117, v134, v145
	v_fmac_f32_e32 v117, v133, v146
	s_waitcnt lgkmcnt(1)
	v_fmac_f32_e32 v116, v131, v136
	v_fmac_f32_e32 v118, v135, v148
	v_fmac_f32_e32 v119, v135, v152
	v_fmac_f32_e32 v117, v132, v147
	ds_read_b128 v[144:147], v90 offset:24672
	v_fmac_f32_e32 v116, v130, v137
	v_fmac_f32_e32 v118, v134, v149
	v_fmac_f32_e32 v119, v134, v153
	v_fmac_f32_e32 v116, v129, v138
	v_fmac_f32_e32 v118, v133, v150
	v_fmac_f32_e32 v119, v133, v154
	v_fmac_f32_e32 v116, v128, v139
	ds_read_b128 v[136:139], v90 offset:20592
	s_waitcnt lgkmcnt(2)
	v_fmac_f32_e32 v117, v131, v140
	v_fmac_f32_e32 v118, v132, v151
	v_fmac_f32_e32 v119, v132, v155
	ds_read_b128 v[132:135], v90 offset:12384
	ds_read_b128 v[148:151], v90 offset:28768
	v_fmac_f32_e32 v117, v130, v141
	v_fmac_f32_e32 v117, v129, v142
	v_fmac_f32_e32 v117, v128, v143
	ds_read_b128 v[140:143], v90 offset:24688
	s_waitcnt lgkmcnt(4)
	v_fmac_f32_e32 v118, v131, v144
	v_fmac_f32_e32 v114, v123, v8
	v_fmac_f32_e32 v118, v130, v145
	v_fmac_f32_e32 v114, v122, v9
	v_fmac_f32_e32 v118, v129, v146
	v_fmac_f32_e32 v114, v121, v10
	v_fmac_f32_e32 v118, v128, v147
	ds_read_b128 v[144:147], v90 offset:28784
	s_waitcnt lgkmcnt(2)
	v_fmac_f32_e32 v119, v131, v148
	v_fmac_f32_e32 v114, v120, v11
	ds_read_b128 v[8:11], v90 offset:8336
	v_fmac_f32_e32 v115, v131, v132
	v_fmac_f32_e32 v115, v130, v133
	v_fmac_f32_e32 v119, v130, v149
	v_fmac_f32_e32 v115, v129, v134
	v_fmac_f32_e32 v119, v129, v150
	v_fmac_f32_e32 v115, v128, v135
	v_fmac_f32_e32 v119, v128, v151
	ds_read_b128 v[128:131], v90 offset:12400
	s_waitcnt lgkmcnt(1)
	v_fmac_f32_e32 v114, v111, v8
	ds_read_b128 v[132:135], v90 offset:16496
	v_fmac_f32_e32 v114, v110, v9
	v_fmac_f32_e32 v114, v109, v10
	v_fmac_f32_e32 v114, v108, v11
	ds_read_b128 v[8:11], v90 offset:8352
	s_waitcnt lgkmcnt(2)
	v_fmac_f32_e32 v115, v127, v128
	v_fmac_f32_e32 v115, v126, v129
	v_fmac_f32_e32 v115, v125, v130
	v_fmac_f32_e32 v115, v124, v131
	ds_read_b128 v[128:131], v90 offset:16512
	s_waitcnt lgkmcnt(2)
	v_fmac_f32_e32 v116, v127, v132
	v_fmac_f32_e32 v116, v126, v133
	v_fmac_f32_e32 v116, v125, v134
	v_fmac_f32_e32 v117, v127, v136
	v_fmac_f32_e32 v116, v124, v135
	ds_read_b128 v[132:135], v90 offset:20608
	v_fmac_f32_e32 v117, v126, v137
	v_fmac_f32_e32 v117, v125, v138
	s_waitcnt lgkmcnt(1)
	v_fmac_f32_e32 v116, v123, v128
	v_fmac_f32_e32 v118, v127, v140
	v_fmac_f32_e32 v119, v127, v144
	v_fmac_f32_e32 v117, v124, v139
	ds_read_b128 v[136:139], v90 offset:24704
	v_fmac_f32_e32 v116, v122, v129
	v_fmac_f32_e32 v118, v126, v141
	v_fmac_f32_e32 v119, v126, v145
	v_fmac_f32_e32 v116, v121, v130
	v_fmac_f32_e32 v118, v125, v142
	v_fmac_f32_e32 v119, v125, v146
	v_fmac_f32_e32 v116, v120, v131
	ds_read_b128 v[128:131], v90 offset:20624
	s_waitcnt lgkmcnt(2)
	v_fmac_f32_e32 v117, v123, v132
	v_fmac_f32_e32 v118, v124, v143
	v_fmac_f32_e32 v119, v124, v147
	ds_read_b128 v[124:127], v90 offset:12416
	ds_read_b128 v[140:143], v90 offset:28800
	v_fmac_f32_e32 v117, v122, v133
	v_fmac_f32_e32 v117, v121, v134
	v_fmac_f32_e32 v117, v120, v135
	ds_read_b128 v[132:135], v90 offset:24720
	s_waitcnt lgkmcnt(4)
	v_fmac_f32_e32 v118, v123, v136
	v_fmac_f32_e32 v114, v107, v8
	v_fmac_f32_e32 v118, v122, v137
	v_fmac_f32_e32 v114, v106, v9
	v_fmac_f32_e32 v118, v121, v138
	v_fmac_f32_e32 v114, v105, v10
	v_fmac_f32_e32 v118, v120, v139
	ds_read_b128 v[136:139], v90 offset:28816
	s_waitcnt lgkmcnt(2)
	v_fmac_f32_e32 v119, v123, v140
	v_fmac_f32_e32 v114, v104, v11
	ds_read_b128 v[8:11], v90 offset:8368
	v_fmac_f32_e32 v115, v123, v124
	v_fmac_f32_e32 v115, v122, v125
	v_fmac_f32_e32 v119, v122, v141
	v_fmac_f32_e32 v115, v121, v126
	v_fmac_f32_e32 v119, v121, v142
	v_fmac_f32_e32 v115, v120, v127
	v_fmac_f32_e32 v119, v120, v143
	ds_read_b128 v[120:123], v90 offset:12432
	s_waitcnt lgkmcnt(1)
	v_fmac_f32_e32 v114, v103, v8
	ds_read_b128 v[124:127], v90 offset:16528
	v_fmac_f32_e32 v114, v102, v9
	v_fmac_f32_e32 v114, v101, v10
	v_fmac_f32_e32 v114, v100, v11
	ds_read_b128 v[8:11], v90 offset:8384
	s_waitcnt lgkmcnt(2)
	v_fmac_f32_e32 v115, v111, v120
	v_fmac_f32_e32 v115, v110, v121
	v_fmac_f32_e32 v115, v109, v122
	v_fmac_f32_e32 v115, v108, v123
	ds_read_b128 v[120:123], v90 offset:16544
	s_waitcnt lgkmcnt(2)
	v_fmac_f32_e32 v116, v111, v124
	v_fmac_f32_e32 v116, v110, v125
	v_fmac_f32_e32 v116, v109, v126
	v_fmac_f32_e32 v117, v111, v128
	v_fmac_f32_e32 v116, v108, v127
	ds_read_b128 v[124:127], v90 offset:20640
	v_fmac_f32_e32 v117, v110, v129
	v_fmac_f32_e32 v117, v109, v130
	s_waitcnt lgkmcnt(1)
	v_fmac_f32_e32 v116, v107, v120
	v_fmac_f32_e32 v118, v111, v132
	v_fmac_f32_e32 v119, v111, v136
	v_fmac_f32_e32 v117, v108, v131
	ds_read_b128 v[128:131], v90 offset:24736
	v_fmac_f32_e32 v116, v106, v121
	v_fmac_f32_e32 v118, v110, v133
	v_fmac_f32_e32 v119, v110, v137
	v_fmac_f32_e32 v116, v105, v122
	v_fmac_f32_e32 v118, v109, v134
	v_fmac_f32_e32 v119, v109, v138
	v_fmac_f32_e32 v116, v104, v123
	ds_read_b128 v[120:123], v90 offset:20656
	s_waitcnt lgkmcnt(2)
	v_fmac_f32_e32 v117, v107, v124
	v_fmac_f32_e32 v118, v108, v135
	v_fmac_f32_e32 v119, v108, v139
	ds_read_b128 v[108:111], v90 offset:12448
	ds_read_b128 v[132:135], v90 offset:28832
	v_fmac_f32_e32 v117, v106, v125
	v_fmac_f32_e32 v117, v105, v126
	v_fmac_f32_e32 v117, v104, v127
	ds_read_b128 v[124:127], v90 offset:24752
	s_waitcnt lgkmcnt(4)
	v_fmac_f32_e32 v118, v107, v128
	v_fmac_f32_e32 v114, v99, v8
	v_fmac_f32_e32 v118, v106, v129
	v_fmac_f32_e32 v114, v98, v9
	v_fmac_f32_e32 v118, v105, v130
	v_fmac_f32_e32 v114, v97, v10
	v_fmac_f32_e32 v118, v104, v131
	ds_read_b128 v[128:131], v90 offset:28848
	s_waitcnt lgkmcnt(2)
	v_fmac_f32_e32 v119, v107, v132
	v_fmac_f32_e32 v114, v96, v11
	ds_read_b128 v[8:11], v90 offset:8400
	v_fmac_f32_e32 v115, v107, v108
	v_fmac_f32_e32 v115, v106, v109
	v_fmac_f32_e32 v119, v106, v133
	v_fmac_f32_e32 v115, v105, v110
	v_fmac_f32_e32 v119, v105, v134
	v_fmac_f32_e32 v115, v104, v111
	v_fmac_f32_e32 v119, v104, v135
	ds_read_b128 v[104:107], v90 offset:12464
	s_waitcnt lgkmcnt(1)
	v_fmac_f32_e32 v114, v95, v8
	ds_read_b128 v[108:111], v90 offset:16560
	v_fmac_f32_e32 v114, v77, v9
	v_fmac_f32_e32 v114, v76, v10
	v_fmac_f32_e32 v114, v75, v11
	ds_read_b128 v[8:11], v90 offset:8416
	s_waitcnt lgkmcnt(2)
	v_fmac_f32_e32 v115, v103, v104
	v_fmac_f32_e32 v115, v102, v105
	v_fmac_f32_e32 v115, v101, v106
	v_fmac_f32_e32 v115, v100, v107
	ds_read_b128 v[104:107], v90 offset:16576
	s_waitcnt lgkmcnt(2)
	v_fmac_f32_e32 v116, v103, v108
	v_fmac_f32_e32 v116, v102, v109
	v_fmac_f32_e32 v116, v101, v110
	v_fmac_f32_e32 v117, v103, v120
	v_fmac_f32_e32 v116, v100, v111
	ds_read_b128 v[108:111], v90 offset:20672
	v_fmac_f32_e32 v117, v102, v121
	v_fmac_f32_e32 v117, v101, v122
	s_waitcnt lgkmcnt(1)
	v_fmac_f32_e32 v116, v99, v104
	v_fmac_f32_e32 v118, v103, v124
	v_fmac_f32_e32 v119, v103, v128
	v_fmac_f32_e32 v117, v100, v123
	ds_read_b128 v[120:123], v90 offset:24768
	v_fmac_f32_e32 v116, v98, v105
	v_fmac_f32_e32 v118, v102, v125
	v_fmac_f32_e32 v119, v102, v129
	v_fmac_f32_e32 v116, v97, v106
	v_fmac_f32_e32 v118, v101, v126
	v_fmac_f32_e32 v119, v101, v130
	v_fmac_f32_e32 v116, v96, v107
	ds_read_b128 v[104:107], v90 offset:20688
	s_waitcnt lgkmcnt(2)
	v_fmac_f32_e32 v117, v99, v108
	v_fmac_f32_e32 v118, v100, v127
	v_fmac_f32_e32 v119, v100, v131
	ds_read_b128 v[100:103], v90 offset:12480
	ds_read_b128 v[124:127], v90 offset:28864
	v_fmac_f32_e32 v117, v98, v109
	v_fmac_f32_e32 v117, v97, v110
	v_fmac_f32_e32 v117, v96, v111
	ds_read_b128 v[108:111], v90 offset:24784
	s_waitcnt lgkmcnt(4)
	v_fmac_f32_e32 v118, v99, v120
	v_fmac_f32_e32 v114, v74, v8
	v_fmac_f32_e32 v118, v98, v121
	v_fmac_f32_e32 v114, v73, v9
	v_fmac_f32_e32 v118, v97, v122
	v_fmac_f32_e32 v114, v72, v10
	v_fmac_f32_e32 v118, v96, v123
	ds_read_b128 v[120:123], v90 offset:28880
	s_waitcnt lgkmcnt(2)
	v_fmac_f32_e32 v119, v99, v124
	v_fmac_f32_e32 v114, v65, v11
	ds_read_b128 v[8:11], v90 offset:8432
	v_fmac_f32_e32 v115, v99, v100
	v_fmac_f32_e32 v115, v98, v101
	v_fmac_f32_e32 v119, v98, v125
	v_fmac_f32_e32 v115, v97, v102
	v_fmac_f32_e32 v119, v97, v126
	v_fmac_f32_e32 v115, v96, v103
	v_fmac_f32_e32 v119, v96, v127
	ds_read_b128 v[96:99], v90 offset:12496
	ds_read_b128 v[100:103], v90 offset:16592
	v_fmac_f32_e32 v117, v95, v104
	v_fmac_f32_e32 v117, v77, v105
	v_fmac_f32_e32 v117, v76, v106
	s_waitcnt lgkmcnt(1)
	v_fmac_f32_e32 v115, v95, v96
	s_waitcnt lgkmcnt(0)
	v_fmac_f32_e32 v116, v95, v100
	v_fmac_f32_e32 v115, v77, v97
	v_fmac_f32_e32 v116, v77, v101
	v_fmac_f32_e32 v115, v76, v98
	v_fmac_f32_e32 v116, v76, v102
	v_fmac_f32_e32 v115, v75, v99
	v_fmac_f32_e32 v116, v75, v103
	ds_read_b128 v[96:99], v90 offset:12512
	ds_read_b128 v[100:103], v90 offset:16608
	v_fmac_f32_e32 v118, v95, v108
	v_fmac_f32_e32 v117, v75, v107
	ds_read_b128 v[104:107], v90 offset:20704
	v_fmac_f32_e32 v118, v77, v109
	v_fmac_f32_e32 v118, v76, v110
	s_waitcnt lgkmcnt(1)
	v_fmac_f32_e32 v116, v74, v100
	v_fmac_f32_e32 v119, v95, v120
	v_fmac_f32_e32 v118, v75, v111
	ds_read_b128 v[108:111], v90 offset:24800
	v_fmac_f32_e32 v116, v73, v101
	v_fmac_f32_e32 v119, v77, v121
	v_fmac_f32_e32 v116, v72, v102
	v_fmac_f32_e32 v119, v76, v122
	v_fmac_f32_e32 v116, v65, v103
	ds_read_b128 v[100:103], v90 offset:20720
	s_waitcnt lgkmcnt(2)
	v_fmac_f32_e32 v117, v74, v104
	v_fmac_f32_e32 v119, v75, v123
	ds_read_b128 v[120:123], v90 offset:28896
	v_fmac_f32_e32 v117, v73, v105
	v_fmac_f32_e32 v117, v72, v106
	v_fmac_f32_e32 v117, v65, v107
	ds_read_b128 v[104:107], v90 offset:24816
	s_waitcnt lgkmcnt(3)
	v_fmac_f32_e32 v118, v74, v108
	v_fmac_f32_e32 v118, v73, v109
	v_fmac_f32_e32 v115, v74, v96
	v_fmac_f32_e32 v118, v72, v110
	v_fmac_f32_e32 v115, v73, v97
	v_fmac_f32_e32 v118, v65, v111
	ds_read_b128 v[108:111], v90 offset:28912
	s_waitcnt lgkmcnt(2)
	v_fmac_f32_e32 v119, v74, v120
	v_fmac_f32_e32 v119, v73, v121
	v_fmac_f32_e32 v115, v72, v98
	v_fmac_f32_e32 v119, v72, v122
	v_fmac_f32_e32 v115, v65, v99
	ds_read_b128 v[72:75], v90 offset:12528
	ds_read_b128 v[96:99], v90 offset:16624
	v_fmac_f32_e32 v119, v65, v123
	v_fmac_f32_e32 v112, v18, v0
	v_fmac_f32_e32 v113, v18, v4
	v_fmac_f32_e32 v114, v18, v8
	s_waitcnt lgkmcnt(1)
	v_fmac_f32_e32 v115, v18, v72
	s_waitcnt lgkmcnt(0)
	v_fmac_f32_e32 v116, v18, v96
	v_fmac_f32_e32 v117, v18, v100
	v_fmac_f32_e32 v118, v18, v104
	v_fmac_f32_e32 v119, v18, v108
	v_fmac_f32_e32 v112, v15, v1
	v_fmac_f32_e32 v113, v15, v5
	v_fmac_f32_e32 v114, v15, v9
	v_fmac_f32_e32 v115, v15, v73
	v_fmac_f32_e32 v116, v15, v97
	v_fmac_f32_e32 v117, v15, v101
	v_fmac_f32_e32 v118, v15, v105
	v_fmac_f32_e32 v119, v15, v109
	v_fmac_f32_e32 v112, v14, v2
	v_fmac_f32_e32 v113, v14, v6
	v_fmac_f32_e32 v114, v14, v10
	v_fmac_f32_e32 v115, v14, v74
	v_fmac_f32_e32 v116, v14, v98
	v_fmac_f32_e32 v117, v14, v102
	v_fmac_f32_e32 v118, v14, v106
	v_fmac_f32_e32 v119, v14, v110
	v_fmac_f32_e32 v112, v13, v3
	v_fmac_f32_e32 v113, v13, v7
	v_add_u32_e32 v0, 0x8000, v83
	v_fmac_f32_e32 v114, v13, v11
	v_fmac_f32_e32 v115, v13, v75
	v_fmac_f32_e32 v116, v13, v99
	v_fmac_f32_e32 v117, v13, v103
	v_fmac_f32_e32 v118, v13, v107
	v_fmac_f32_e32 v119, v13, v111
	ds_write2_b32 v0, v112, v113 offset1:32
	ds_write2_b32 v0, v114, v115 offset0:64 offset1:96
	ds_write2_b32 v0, v116, v117 offset0:128 offset1:160
	ds_write2_b32 v0, v118, v119 offset0:192 offset1:224
	s_waitcnt lgkmcnt(0)
	s_barrier
	s_and_saveexec_b64 s[60:61], s[6:7]
	s_cbranch_execz .LBB0_22
	s_mul_i32 s57, s56, 0xc00
	v_add_u32_e32 v0, s57, v12
	v_ashrrev_i32_e32 v1, 31, v0
	v_lshl_add_u64 v[0:1], v[0:1], 2, s[44:45]
	global_load_dword v2, v[0:1], off
	ds_read2st64_b32 v[0:1], v82 offset0:128 offset1:132
	s_waitcnt vmcnt(0) lgkmcnt(0)
	v_add_f32_e32 v0, v2, v0
	v_add_f32_e32 v2, v0, v1
	ds_read2st64_b32 v[0:1], v82 offset0:136 offset1:140
	s_waitcnt lgkmcnt(0)
	v_add_f32_e32 v0, v2, v0
	v_add_f32_e32 v2, v0, v1
	ds_read2st64_b32 v[0:1], v82 offset0:144 offset1:148
	s_waitcnt lgkmcnt(0)
	v_add_f32_e32 v0, v2, v0
	v_add_f32_e32 v2, v0, v1
	ds_read2st64_b32 v[0:1], v82 offset0:152 offset1:156
	s_waitcnt lgkmcnt(0)
	v_add_f32_e32 v0, v2, v0
	v_add_f32_e32 v2, v0, v1
	ds_read2st64_b32 v[0:1], v82 offset0:160 offset1:164
	s_waitcnt lgkmcnt(0)
	v_add_f32_e32 v0, v2, v0
	v_add_f32_e32 v2, v0, v1
	ds_read2st64_b32 v[0:1], v82 offset0:168 offset1:172
	s_waitcnt lgkmcnt(0)
	v_add_f32_e32 v0, v2, v0
	v_add_f32_e32 v2, v0, v1
	ds_read2st64_b32 v[0:1], v82 offset0:176 offset1:180
	s_waitcnt lgkmcnt(0)
	v_add_f32_e32 v0, v2, v0
	v_add_f32_e32 v2, v0, v1
	ds_read2st64_b32 v[0:1], v82 offset0:184 offset1:188
	s_waitcnt lgkmcnt(0)
	v_add_f32_e32 v0, v2, v0
	v_add_f32_e32 v2, v0, v1
	v_lshl_add_u32 v0, s56, 3, v81
	s_movk_i32 s56, 0xc00
	v_mad_u64_u32 v[0:1], s[56:57], v0, s56, v[12:13]
	v_ashrrev_i32_e32 v1, 31, v0
	v_lshl_add_u64 v[0:1], v[0:1], 2, s[28:29]
	global_store_dword v[0:1], v2, off
	s_branch .LBB0_22
